# P0 two-class rotation with the class bit taken from blockIdx bit 3 (each XCD gets half x-first and half x-last workgroups)
# baseline (speedup 1.0000x reference)
.LBB0_10:
	s_or_b64 exec, exec, s[2:3]
	s_load_dwordx16 s[72:87], s[0:1], 0x40
	v_readlane_b32 s0, v254, 5
	s_lshr_b32 s89, s0, 6
	v_readlane_b32 s0, v254, 9
	v_readlane_b32 s1, v254, 10
	v_readlane_b32 s2, v254, 11
	v_readlane_b32 s3, v254, 12
	s_cmp_lt_i32 s0, 1
	s_cselect_b64 s[2:3], -1, 0
	s_cmp_gt_i32 s1, 0
	s_cselect_b64 s[0:1], -1, 0
	v_writelane_b32 v254, s2, 31
	s_and_b64 s[6:7], s[2:3], s[0:1]
	s_andn2_b64 vcc, exec, s[6:7]
	v_and_b32_e32 v227, 63, v226
	v_writelane_b32 v254, s3, 32
	s_cbranch_vccnz .LBB0_183
	s_bfe_u32 s99, s88, 0x10003
	s_sub_u32 s99, 2, s99
	s_cmp_eq_u32 s99, 0
	s_cbranch_scc1 .Lp0_front
	s_cmp_eq_u32 s99, 1
	s_cbranch_scc1 .LBB0_163
	s_mov_b32 s99, 3
	s_lshl_b32 s0, s88, 3
	s_add_i32 s8, s89, s0
	s_lshl_b32 s10, s90, 3
	s_branch .LBB0_158
